# row-norm phases (P7, P11): sample-row waves hand their last two prompt rows to 256 other waves
# speedup vs baseline: 1.0142x; 1.0124x over previous
.LBB0_1005:
	v_readlane_b32 s2, v248, 0
	v_readlane_b32 s3, v248, 1
	s_cmp_lt_i32 s2, 8
	s_cselect_b64 s[2:3], -1, 0
	s_and_b64 s[2:3], s[2:3], s[0:1]
	s_andn2_b64 vcc, exec, s[2:3]
	s_cbranch_vccnz .LBB0_1019
	v_lshl_or_b32 v34, s82, 3, v210
	s_movk_i32 s0, 0x4080
	v_cmp_gt_i32_e32 vcc, s0, v34
	s_and_saveexec_b64 s[4:5], vcc
	s_cbranch_execz .LBB0_1018
	v_lshlrev_b32_e32 v1, 2, v0
	v_and_b32_e32 v18, 0xfc, v1
	v_lshlrev_b32_e32 v36, 2, v18
	global_load_dwordx4 v[2:5], v36, s[80:81]
	global_load_dwordx4 v[6:9], v36, s[80:81] offset:1024
	global_load_dwordx4 v[10:13], v36, s[80:81] offset:2048
	global_load_dwordx4 v[14:17], v36, s[80:81] offset:3072
	v_mbcnt_lo_u32_b32 v1, -1, 0
	v_mbcnt_hi_u32_b32 v19, -1, v1
	v_and_b32_e32 v22, 64, v19
	v_xor_b32_e32 v1, 1, v19
	v_add_u32_e32 v22, 64, v22
	v_cmp_lt_i32_e32 vcc, v1, v22
	v_xor_b32_e32 v23, 2, v19
	v_readlane_b32 s8, v248, 2
	v_cndmask_b32_e32 v1, v19, v1, vcc
	v_cmp_lt_i32_e32 vcc, v23, v22
	v_mov_b32_e32 v37, 0
	v_readlane_b32 s9, v248, 3
	v_cndmask_b32_e32 v23, v19, v23, vcc
	v_lshlrev_b32_e32 v46, 2, v23
	v_xor_b32_e32 v23, 4, v19
	v_cmp_lt_i32_e32 vcc, v23, v22
	v_readlane_b32 s10, v248, 4
	v_readlane_b32 s11, v248, 5
	v_cndmask_b32_e32 v23, v19, v23, vcc
	v_lshlrev_b32_e32 v47, 2, v23
	v_xor_b32_e32 v23, 8, v19
	v_cmp_lt_i32_e32 vcc, v23, v22
	s_cmp_lg_u64 s[10:11], 0
	v_lshl_add_u64 v[20:21], s[94:95], 0, v[36:37]
	v_cndmask_b32_e32 v23, v19, v23, vcc
	v_lshlrev_b32_e32 v48, 2, v23
	v_xor_b32_e32 v23, 16, v19
	v_cmp_lt_i32_e32 vcc, v23, v22
	s_mov_b64 s[8:9], 0xb3d6400
	v_lshl_add_u64 v[40:41], s[92:93], 0, v[36:37]
	v_cndmask_b32_e32 v23, v19, v23, vcc
	v_lshlrev_b32_e32 v49, 2, v23
	v_xor_b32_e32 v23, 32, v19
	v_lshlrev_b32_e32 v36, 1, v18
	v_cmp_lt_i32_e32 vcc, v23, v22
	s_cselect_b64 s[0:1], -1, 0
	v_lshl_add_u64 v[38:39], v[20:21], 0, s[8:9]
	v_lshl_add_u64 v[20:21], s[94:95], 0, v[36:37]
	s_mov_b64 s[8:9], 0xbf0cc00
	v_cndmask_b32_e32 v19, v19, v23, vcc
	v_readlane_b32 s12, v248, 6
	v_readlane_b32 s13, v248, 7
	v_readlane_b32 s14, v248, 8
	v_readlane_b32 s15, v248, 9
	v_readlane_b32 s16, v248, 10
	v_readlane_b32 s17, v248, 11
	v_readlane_b32 s18, v248, 12
	v_readlane_b32 s19, v248, 13
	v_readlane_b32 s20, v248, 14
	v_readlane_b32 s21, v248, 15
	v_readlane_b32 s22, v248, 16
	v_lshl_add_u64 v[42:43], v[20:21], 0, s[8:9]
	v_lshlrev_b32_e32 v50, 2, v19
	s_mov_b64 s[8:9], 0x1f80000
	v_cndmask_b32_e64 v19, 0, 1, s[0:1]
	s_mov_b64 s[6:7], 0
	v_lshlrev_b32_e32 v1, 2, v1
	v_lshl_add_u64 v[44:45], v[20:21], 0, s[8:9]
	s_waitcnt lgkmcnt(0)
	s_lshl_b32 s12, s96, 3
	s_movk_i32 s13, 0x3fff
	v_cmp_ne_u32_e64 s[0:1], 1, v19
	v_lshlrev_b32_e32 v36, 2, v18
	s_mov_b32 s14, 0x80000
	s_mov_b32 s15, 0x100000
	s_mov_b32 s16, 0x180000
	s_mov_b32 s17, 0x200000
	s_mov_b32 s18, 0x280000
	s_mov_b32 s19, 0x300000
	s_mov_b32 s20, 0x380000
	v_mov_b32_e32 v51, 0x3727c5ac
	s_mov_b32 s21, 0x800000
	s_movk_i32 s22, 0x407f
	v_readlane_b32 s23, v248, 17
	v_add_u32_e32 v216, 0xffffff80, v34
	v_and_b32_e32 v217, 0x7f, v216
	v_lshrrev_b32_e32 v218, 7, v216
	v_lshl_add_u32 v217, v218, 11, v217
	v_add_u32_e32 v217, 0x3000, v217
	v_mov_b32_e32 v212, -1
	v_mov_b32_e32 v214, -1
	v_mov_b32_e32 v215, 0x7fffffff
	v_mov_b32_e32 v213, v217
	v_add_u32_e32 v218, 0x4000, v34
	v_add_u32_e32 v219, 0x800, v217
	v_cmp_gt_u32_e32 vcc, 0x100, v216
	s_nop 1
	v_cndmask_b32_e32 v212, v212, v218, vcc
	v_cndmask_b32_e32 v214, v214, v219, vcc
	v_add_u32_e32 v219, 0x3000, v34
	v_cmp_gt_u32_e32 vcc, 0x80, v34
	s_nop 1
	v_cndmask_b32_e32 v212, v212, v219, vcc
	v_cndmask_b32_e32 v213, v213, v218, vcc
	s_branch .LBB0_1009
.LBB0_1008:
	s_or_b64 exec, exec, s[8:9]
	v_pk_mul_f32 v[64:65], v[30:31], v[30:31]
	v_pk_mul_f32 v[66:67], v[26:27], v[26:27]
	v_pk_mul_f32 v[60:61], v[32:33], v[32:33]
	v_pk_mul_f32 v[62:63], v[28:29], v[28:29]
	v_mov_b32_e32 v68, v64
	v_mov_b32_e32 v69, v66
	v_mov_b32_e32 v66, v65
	v_pk_add_f32 v[64:65], v[68:69], v[66:67]
	v_mov_b32_e32 v66, v60
	v_mov_b32_e32 v67, v62
	v_pk_mul_f32 v[56:57], v[18:19], v[18:19]
	v_pk_mul_f32 v[58:59], v[22:23], v[22:23]
	v_pk_add_f32 v[64:65], v[66:67], v[64:65]
	v_mov_b32_e32 v62, v61
	v_pk_mul_f32 v[52:53], v[20:21], v[20:21]
	v_pk_mul_f32 v[54:55], v[24:25], v[24:25]
	v_pk_add_f32 v[60:61], v[62:63], v[64:65]
	v_mov_b32_e32 v62, v56
	v_mov_b32_e32 v63, v58
	v_mov_b32_e32 v58, v57
	v_pk_add_f32 v[56:57], v[62:63], v[58:59]
	v_mov_b32_e32 v58, v52
	v_mov_b32_e32 v59, v54
	v_pk_add_f32 v[56:57], v[58:59], v[56:57]
	v_mov_b32_e32 v54, v53
	v_pk_add_f32 v[52:53], v[54:55], v[56:57]
	v_add_f32_e32 v54, v60, v61
	v_add_f32_e32 v53, v53, v54
	v_add_f32_e32 v52, v52, v53
	ds_bpermute_b32 v53, v1, v52
	s_waitcnt lgkmcnt(0)
	v_add_f32_e32 v52, v52, v53
	ds_bpermute_b32 v53, v46, v52
	s_waitcnt lgkmcnt(0)
	v_add_f32_e32 v52, v52, v53
	ds_bpermute_b32 v53, v47, v52
	s_waitcnt lgkmcnt(0)
	v_add_f32_e32 v52, v52, v53
	ds_bpermute_b32 v53, v48, v52
	s_waitcnt lgkmcnt(0)
	v_add_f32_e32 v52, v52, v53
	ds_bpermute_b32 v53, v49, v52
	s_waitcnt lgkmcnt(0)
	v_add_f32_e32 v52, v52, v53
	ds_bpermute_b32 v53, v50, v52
	s_waitcnt lgkmcnt(0)
	v_add_f32_e32 v52, v52, v53
	v_fmamk_f32 v52, v52, 0x3a800000, v51
	v_mul_f32_e32 v53, 0x4b800000, v52
	v_cmp_gt_f32_e32 vcc, s21, v52
	s_nop 1
	v_cndmask_b32_e32 v52, v52, v53, vcc
	v_rsq_f32_e32 v54, v52
	v_lshlrev_b64 v[52:53], 11, v[34:35]
	v_add_u32_e32 v34, s12, v34
	v_lshl_add_u64 v[52:53], v[44:45], 0, v[52:53]
	v_mul_f32_e32 v35, 0x45800000, v54
	v_cndmask_b32_e32 v54, v54, v35, vcc
	v_pk_mul_f32 v[30:31], v[30:31], v[54:55] op_sel_hi:[1,0]
	v_pk_mul_f32 v[32:33], v[32:33], v[54:55] op_sel_hi:[1,0]
	v_pk_mul_f32 v[26:27], v[26:27], v[54:55] op_sel_hi:[1,0]
	v_pk_mul_f32 v[28:29], v[28:29], v[54:55] op_sel_hi:[1,0]
	v_pk_mul_f32 v[22:23], v[22:23], v[54:55] op_sel_hi:[1,0]
	v_pk_mul_f32 v[24:25], v[24:25], v[54:55] op_sel_hi:[1,0]
	v_pk_mul_f32 v[18:19], v[18:19], v[54:55] op_sel_hi:[1,0]
	v_pk_mul_f32 v[20:21], v[20:21], v[54:55] op_sel_hi:[1,0]
	s_waitcnt vmcnt(0)
	v_pk_mul_f32 v[32:33], v[4:5], v[32:33]
	v_pk_mul_f32 v[30:31], v[2:3], v[30:31]
	v_pk_mul_f32 v[28:29], v[8:9], v[28:29]
	v_pk_mul_f32 v[26:27], v[6:7], v[26:27]
	v_pk_mul_f32 v[24:25], v[12:13], v[24:25]
	v_pk_mul_f32 v[22:23], v[10:11], v[22:23]
	v_pk_mul_f32 v[20:21], v[16:17], v[20:21]
	v_pk_mul_f32 v[18:19], v[14:15], v[18:19]
	v_cmp_eq_u32_e32 vcc, v34, v212
	s_nop 1
	v_cndmask_b32_e32 v34, v34, v213, vcc
	v_cmp_eq_u32_e32 vcc, v34, v214
	s_nop 1
	v_cndmask_b32_e32 v34, v34, v215, vcc
	v_cmp_lt_i32_e32 vcc, s22, v34
	v_cvt_pk_bf16_f32 v30, v30, v31
	v_cvt_pk_bf16_f32 v31, v32, v33
	v_cvt_pk_bf16_f32 v26, v26, v27
	v_cvt_pk_bf16_f32 v27, v28, v29
	v_cvt_pk_bf16_f32 v22, v22, v23
	v_cvt_pk_bf16_f32 v23, v24, v25
	v_cvt_pk_bf16_f32 v18, v18, v19
	v_cvt_pk_bf16_f32 v19, v20, v21
	s_or_b64 s[6:7], vcc, s[6:7]
	global_store_dwordx2 v[52:53], v[30:31], off
	global_store_dwordx2 v[52:53], v[26:27], off offset:512
	global_store_dwordx2 v[52:53], v[22:23], off offset:1024
	global_store_dwordx2 v[52:53], v[18:19], off offset:1536
	s_andn2_b64 exec, exec, s[6:7]
	s_cbranch_execz .LBB0_1018

.LBB0_1262:
	v_readlane_b32 s2, v248, 0
	v_readlane_b32 s3, v248, 1
	s_cmp_lt_i32 s2, 12
	s_cselect_b64 s[2:3], -1, 0
	s_and_b64 s[0:1], s[2:3], s[0:1]
	s_andn2_b64 vcc, exec, s[0:1]
	s_cbranch_vccnz .LBB0_1270
	v_lshl_or_b32 v16, s82, 3, v210
	s_movk_i32 s0, 0x4080
	v_cmp_gt_i32_e32 vcc, s0, v16
	s_and_saveexec_b64 s[0:1], vcc
	s_cbranch_execz .LBB0_1270
	v_lshlrev_b32_e32 v0, 2, v0
	v_and_b32_e32 v17, 0xfc, v0
	v_lshlrev_b32_e32 v18, 2, v17
	global_load_dwordx4 v[0:3], v18, s[90:91]
	global_load_dwordx4 v[4:7], v18, s[90:91] offset:1024
	global_load_dwordx4 v[8:11], v18, s[90:91] offset:2048
	global_load_dwordx4 v[12:15], v18, s[90:91] offset:3072
	v_lshlrev_b32_e32 v22, 1, v17
	v_mbcnt_lo_u32_b32 v17, -1, 0
	v_mbcnt_hi_u32_b32 v17, -1, v17
	v_and_b32_e32 v25, 64, v17
	v_xor_b32_e32 v24, 1, v17
	v_add_u32_e32 v25, 64, v25
	v_cmp_lt_i32_e32 vcc, v24, v25
	v_mov_b32_e32 v19, 0
	v_lshl_add_u64 v[20:21], s[94:95], 0, v[18:19]
	v_cndmask_b32_e32 v24, v17, v24, vcc
	v_lshlrev_b32_e32 v44, 2, v24
	v_xor_b32_e32 v24, 2, v17
	v_cmp_lt_i32_e32 vcc, v24, v25
	s_mov_b64 s[0:1], 0xb3d6400
	v_mov_b32_e32 v23, v19
	v_cndmask_b32_e32 v24, v17, v24, vcc
	v_lshlrev_b32_e32 v45, 2, v24
	v_xor_b32_e32 v24, 4, v17
	v_cmp_lt_i32_e32 vcc, v24, v25
	v_lshl_add_u64 v[20:21], v[20:21], 0, s[0:1]
	v_lshl_add_u64 v[22:23], s[94:95], 0, v[22:23]
	v_cndmask_b32_e32 v24, v17, v24, vcc
	v_lshlrev_b32_e32 v46, 2, v24
	v_xor_b32_e32 v24, 8, v17
	v_cmp_lt_i32_e32 vcc, v24, v25
	s_mov_b64 s[0:1], 0x1f80000
	v_lshl_add_u64 v[22:23], v[22:23], 0, s[0:1]
	v_cndmask_b32_e32 v24, v17, v24, vcc
	v_lshlrev_b32_e32 v47, 2, v24
	v_xor_b32_e32 v24, 16, v17
	v_cmp_lt_i32_e32 vcc, v24, v25
	s_waitcnt lgkmcnt(0)
	s_lshl_b32 s4, s96, 3
	s_mov_b64 s[0:1], 0
	v_cndmask_b32_e32 v24, v17, v24, vcc
	v_lshlrev_b32_e32 v48, 2, v24
	v_xor_b32_e32 v24, 32, v17
	v_cmp_lt_i32_e32 vcc, v24, v25
	s_movk_i32 s5, 0x3fff
	v_mov_b32_e32 v50, 0x3727c5ac
	v_cndmask_b32_e32 v17, v17, v24, vcc
	v_lshlrev_b32_e32 v49, 2, v17
	v_lshl_add_u64 v[24:25], s[92:93], 0, v[18:19]
	s_mov_b32 s6, 0x800000
	s_movk_i32 s7, 0x407f
	v_add_u32_e32 v232, 0xffffff80, v16
	v_and_b32_e32 v233, 0x7f, v232
	v_lshrrev_b32_e32 v234, 7, v232
	v_lshl_add_u32 v233, v234, 11, v233
	v_add_u32_e32 v233, 0x3000, v233
	v_mov_b32_e32 v228, -1
	v_mov_b32_e32 v230, -1
	v_mov_b32_e32 v231, 0x7fffffff
	v_mov_b32_e32 v229, v233
	v_add_u32_e32 v234, 0x4000, v16
	v_add_u32_e32 v235, 0x800, v233
	v_cmp_gt_u32_e32 vcc, 0x100, v232
	s_nop 1
	v_cndmask_b32_e32 v228, v228, v234, vcc
	v_cndmask_b32_e32 v230, v230, v235, vcc
	v_add_u32_e32 v235, 0x3000, v16
	v_cmp_gt_u32_e32 vcc, 0x80, v16
	s_nop 1
	v_cndmask_b32_e32 v228, v228, v235, vcc
	v_cndmask_b32_e32 v229, v229, v234, vcc
	s_branch .LBB0_1266
.LBB0_1265:
	s_or_b64 exec, exec, s[2:3]
	v_pk_mul_f32 v[64:65], v[42:43], v[42:43]
	v_pk_mul_f32 v[66:67], v[38:39], v[38:39]
	v_pk_mul_f32 v[60:61], v[40:41], v[40:41]
	v_pk_mul_f32 v[62:63], v[36:37], v[36:37]
	v_mov_b32_e32 v68, v64
	v_mov_b32_e32 v69, v66
	v_mov_b32_e32 v66, v65
	v_pk_add_f32 v[64:65], v[68:69], v[66:67]
	v_mov_b32_e32 v66, v60
	v_mov_b32_e32 v67, v62
	v_pk_mul_f32 v[56:57], v[30:31], v[30:31]
	v_pk_mul_f32 v[58:59], v[34:35], v[34:35]
	v_pk_add_f32 v[64:65], v[66:67], v[64:65]
	v_mov_b32_e32 v62, v61
	v_pk_mul_f32 v[52:53], v[28:29], v[28:29]
	v_pk_mul_f32 v[54:55], v[32:33], v[32:33]
	v_pk_add_f32 v[60:61], v[62:63], v[64:65]
	v_mov_b32_e32 v62, v56
	v_mov_b32_e32 v63, v58
	v_mov_b32_e32 v58, v57
	v_pk_add_f32 v[56:57], v[62:63], v[58:59]
	v_mov_b32_e32 v58, v52
	v_mov_b32_e32 v59, v54
	v_pk_add_f32 v[56:57], v[58:59], v[56:57]
	v_mov_b32_e32 v54, v53
	v_pk_add_f32 v[52:53], v[54:55], v[56:57]
	v_add_f32_e32 v17, v60, v61
	v_add_f32_e32 v17, v53, v17
	v_add_f32_e32 v17, v52, v17
	ds_bpermute_b32 v18, v44, v17
	v_lshl_add_u64 v[52:53], v[24:25], 0, v[26:27]
	v_add_u32_e32 v16, s4, v16
	s_waitcnt lgkmcnt(0)
	v_add_f32_e32 v17, v17, v18
	ds_bpermute_b32 v18, v45, v17
	s_waitcnt lgkmcnt(0)
	v_add_f32_e32 v17, v17, v18
	ds_bpermute_b32 v18, v46, v17
	s_waitcnt lgkmcnt(0)
	v_add_f32_e32 v17, v17, v18
	ds_bpermute_b32 v18, v47, v17
	s_waitcnt lgkmcnt(0)
	v_add_f32_e32 v17, v17, v18
	ds_bpermute_b32 v18, v48, v17
	s_waitcnt lgkmcnt(0)
	v_add_f32_e32 v17, v17, v18
	ds_bpermute_b32 v18, v49, v17
	s_waitcnt lgkmcnt(0)
	v_add_f32_e32 v17, v17, v18
	v_fmamk_f32 v17, v17, 0x3a800000, v50
	v_mul_f32_e32 v18, 0x4b800000, v17
	v_cmp_gt_f32_e32 vcc, s6, v17
	s_nop 1
	v_cndmask_b32_e32 v17, v17, v18, vcc
	v_rsq_f32_e32 v17, v17
	s_nop 0
	v_mul_f32_e32 v18, 0x45800000, v17
	v_cndmask_b32_e32 v18, v17, v18, vcc
	v_pk_mul_f32 v[26:27], v[42:43], v[18:19] op_sel_hi:[1,0]
	v_pk_mul_f32 v[40:41], v[40:41], v[18:19] op_sel_hi:[1,0]
	v_pk_mul_f32 v[54:55], v[36:37], v[18:19] op_sel_hi:[1,0]
	s_waitcnt vmcnt(0)
	v_pk_mul_f32 v[36:37], v[0:1], v[26:27]
	v_pk_mul_f32 v[26:27], v[34:35], v[18:19] op_sel_hi:[1,0]
	v_pk_mul_f32 v[32:33], v[32:33], v[18:19] op_sel_hi:[1,0]
	v_pk_mul_f32 v[42:43], v[38:39], v[18:19] op_sel_hi:[1,0]
	v_pk_mul_f32 v[38:39], v[2:3], v[40:41]
	v_pk_mul_f32 v[34:35], v[10:11], v[32:33]
	v_pk_mul_f32 v[32:33], v[8:9], v[26:27]
	v_pk_mul_f32 v[26:27], v[30:31], v[18:19] op_sel_hi:[1,0]
	v_pk_mul_f32 v[28:29], v[28:29], v[18:19] op_sel_hi:[1,0]
	v_cmp_eq_u32_e32 vcc, v16, v228
	s_nop 1
	v_cndmask_b32_e32 v16, v16, v229, vcc
	v_cmp_eq_u32_e32 vcc, v16, v230
	s_nop 1
	v_cndmask_b32_e32 v16, v16, v231, vcc
	v_cmp_lt_i32_e32 vcc, s7, v16
	global_store_dwordx4 v[52:53], v[36:39], off nt
	v_pk_mul_f32 v[28:29], v[14:15], v[28:29]
	v_pk_mul_f32 v[26:27], v[12:13], v[26:27]
	v_pk_mul_f32 v[38:39], v[6:7], v[54:55]
	v_pk_mul_f32 v[36:37], v[4:5], v[42:43]
	s_or_b64 s[0:1], vcc, s[0:1]
	global_store_dwordx4 v[52:53], v[36:39], off offset:1024 nt
	global_store_dwordx4 v[52:53], v[32:35], off offset:2048 nt
	global_store_dwordx4 v[52:53], v[26:29], off offset:3072 nt
	s_andn2_b64 exec, exec, s[0:1]
	s_cbranch_execz .LBB0_1270
